# grid barrier: L1 invalidate overlaps the XCD-last leader's L2 write-back; non-last blocks count completed invalidates in a per-XCD counter the leader checks before raising the flag
# speedup vs baseline: 1.0217x; 1.0028x over previous
.LBB0_85:
	s_or_b64 exec, exec, s[8:9]
	s_waitcnt vmcnt(0)
	buffer_inv sc1
	v_readfirstlane_b32 s3, v3
	v_sub_u32_e32 v4, 0, v2
	s_nop 0
	v_add_u32_e32 v3, s3, v1
	v_cvt_f32_u32_e32 v1, v2
	v_rcp_iflag_f32_e32 v1, v1
	s_nop 0
	v_mul_f32_e32 v1, 0x4f7ffffe, v1
	v_cvt_u32_f32_e32 v1, v1
	v_mul_lo_u32 v4, v4, v1
	v_mul_hi_u32 v4, v1, v4
	v_add_u32_e32 v1, v1, v4
	v_mul_hi_u32 v1, v3, v1
	v_mul_lo_u32 v4, v1, v2
	v_sub_u32_e32 v4, v3, v4
	v_cmp_ge_u32_e32 vcc, v4, v2
	v_add_u32_e32 v5, 1, v1
	s_nop 0
	v_cndmask_b32_e32 v1, v1, v5, vcc
	v_sub_u32_e32 v5, v4, v2
	v_cndmask_b32_e32 v4, v4, v5, vcc
	v_cmp_ge_u32_e32 vcc, v4, v2
	v_add_u32_e32 v4, 1, v1
	s_nop 0
	v_cndmask_b32_e32 v1, v1, v4, vcc
	v_add_u32_e32 v4, 1, v3
	v_mad_u64_u32 v[2:3], s[6:7], v2, v1, v[2:3]
	v_cmp_ne_u32_e32 vcc, v4, v2
	s_and_saveexec_b64 s[6:7], vcc
	s_xor_b64 s[6:7], exec, s[6:7]
	s_cbranch_execz .LBB0_99
	s_waitcnt vmcnt(0)
	v_mov_b32_e32 v3, 0x2000
	v_mov_b32_e32 v2, 1
	global_atomic_add v3, v2, s[4:5] offset:1024
	v_mad_u32_u24 v4, v1, v0, v0
	v_mov_b32_e32 v0, 0x3000
	global_load_dword v0, v0, s[92:93] offset:1024 sc1
	s_add_u32 s12, s92, 0x3400
	s_addc_u32 s13, s93, 0
	s_waitcnt vmcnt(0)
	v_cmp_lt_u32_e32 vcc, v0, v4
	s_and_saveexec_b64 s[8:9], vcc
	s_cbranch_execz .LBB0_98
	s_mov_b32 s3, 1
	s_mov_b64 s[56:57], 0
	v_mov_b32_e32 v0, 0
	s_branch .LBB0_89

.LBB0_99:
	s_andn2_saveexec_b64 s[6:7], s[6:7]
	s_cbranch_execz .LBB0_119
	s_mov_b64 s[6:7], exec
	buffer_wbl2 sc1
	v_sub_u32_e32 v3, v2, v1
	v_mov_b32_e32 v4, 0x2000
	v_add_u32_e32 v3, -1, v3
	s_mov_b32 s98, 0x100000
.Lmy_xinv_1:
	global_load_dword v5, v4, s[4:5] offset:1024 sc1
	s_sub_u32 s98, s98, 1
	s_waitcnt lgkmcnt(0)
	s_waitcnt vmcnt(0)
	v_cmp_ge_u32_e32 vcc, v5, v3
	s_cbranch_vccnz .Lmy_xinv_done_1
	s_cmp_lg_u32 s98, 0
	s_cbranch_scc1 .Lmy_xinv_1
.Lmy_xinv_done_1:
	v_mbcnt_lo_u32_b32 v1, s6, 0
	v_mbcnt_hi_u32_b32 v1, s7, v1
	v_cmp_eq_u32_e32 vcc, 0, v1
	s_and_saveexec_b64 s[8:9], vcc
	s_cbranch_execz .LBB0_102
	s_bcnt1_i32_b64 s3, s[6:7]
	v_mov_b32_e32 v2, 0x3000
	v_mov_b32_e32 v3, s3
	global_atomic_add v2, v2, v3, s[92:93] offset:1024 sc0

.LBB0_140:
	s_or_b64 exec, exec, s[12:13]
	s_waitcnt vmcnt(0)
	buffer_inv sc1
	v_readfirstlane_b32 s0, v3
	v_sub_u32_e32 v4, 0, v2
	s_nop 0
	v_add_u32_e32 v3, s0, v1
	v_cvt_f32_u32_e32 v1, v2
	v_rcp_iflag_f32_e32 v1, v1
	s_nop 0
	v_mul_f32_e32 v1, 0x4f7ffffe, v1
	v_cvt_u32_f32_e32 v1, v1
	v_mul_lo_u32 v4, v4, v1
	v_mul_hi_u32 v4, v1, v4
	v_add_u32_e32 v1, v1, v4
	v_mul_hi_u32 v1, v3, v1
	v_mul_lo_u32 v4, v1, v2
	v_sub_u32_e32 v4, v3, v4
	v_cmp_ge_u32_e32 vcc, v4, v2
	v_add_u32_e32 v5, 1, v1
	s_nop 0
	v_cndmask_b32_e32 v1, v1, v5, vcc
	v_sub_u32_e32 v5, v4, v2
	v_cndmask_b32_e32 v4, v4, v5, vcc
	v_cmp_ge_u32_e32 vcc, v4, v2
	v_add_u32_e32 v4, 1, v1
	s_nop 0
	v_cndmask_b32_e32 v1, v1, v4, vcc
	v_add_u32_e32 v4, 1, v3
	v_mad_u64_u32 v[2:3], s[0:1], v2, v1, v[2:3]
	v_cmp_ne_u32_e32 vcc, v4, v2
	s_and_saveexec_b64 s[0:1], vcc
	s_xor_b64 s[8:9], exec, s[0:1]
	s_cbranch_execz .LBB0_154
	s_waitcnt vmcnt(0)
	v_mov_b32_e32 v3, 0x2000
	v_mov_b32_e32 v2, 1
	global_atomic_add v3, v2, s[6:7] offset:1024
	v_mad_u32_u24 v4, v1, v0, v0
	v_mov_b32_e32 v0, 0x3000
	global_load_dword v0, v0, s[92:93] offset:1024 sc1
	s_add_u32 s56, s92, 0x3400
	s_addc_u32 s57, s93, 0
	s_waitcnt vmcnt(0)
	v_cmp_lt_u32_e32 vcc, v0, v4
	s_and_saveexec_b64 s[12:13], vcc
	s_cbranch_execz .LBB0_153
	s_mov_b32 s0, 1
	s_mov_b64 s[60:61], 0
	v_mov_b32_e32 v0, 0
	s_branch .LBB0_144

.LBB0_154:
	s_andn2_saveexec_b64 s[0:1], s[8:9]
	s_cbranch_execz .LBB0_174
	s_mov_b64 s[8:9], exec
	buffer_wbl2 sc1
	v_sub_u32_e32 v3, v2, v1
	v_mov_b32_e32 v4, 0x2000
	v_add_u32_e32 v3, -1, v3
	s_mov_b32 s98, 0x100000
.Lmy_xinv_2:
	global_load_dword v5, v4, s[6:7] offset:1024 sc1
	s_sub_u32 s98, s98, 1
	s_waitcnt lgkmcnt(0)
	s_waitcnt vmcnt(0)
	v_cmp_ge_u32_e32 vcc, v5, v3
	s_cbranch_vccnz .Lmy_xinv_done_2
	s_cmp_lg_u32 s98, 0
	s_cbranch_scc1 .Lmy_xinv_2
.Lmy_xinv_done_2:
	v_mbcnt_lo_u32_b32 v1, s8, 0
	v_mbcnt_hi_u32_b32 v1, s9, v1
	v_cmp_eq_u32_e32 vcc, 0, v1
	s_and_saveexec_b64 s[12:13], vcc
	s_cbranch_execz .LBB0_157
	s_bcnt1_i32_b64 s0, s[8:9]
	v_mov_b32_e32 v2, 0x3000
	v_mov_b32_e32 v3, s0
	global_atomic_add v2, v2, v3, s[92:93] offset:1024 sc0

.LBB0_241:
	s_or_b64 exec, exec, s[12:13]
	s_waitcnt vmcnt(0)
	buffer_inv sc1
	v_readfirstlane_b32 s0, v3
	v_sub_u32_e32 v4, 0, v2
	s_nop 0
	v_add_u32_e32 v3, s0, v1
	v_cvt_f32_u32_e32 v1, v2
	v_rcp_iflag_f32_e32 v1, v1
	s_nop 0
	v_mul_f32_e32 v1, 0x4f7ffffe, v1
	v_cvt_u32_f32_e32 v1, v1
	v_mul_lo_u32 v4, v4, v1
	v_mul_hi_u32 v4, v1, v4
	v_add_u32_e32 v1, v1, v4
	v_mul_hi_u32 v1, v3, v1
	v_mul_lo_u32 v4, v1, v2
	v_sub_u32_e32 v4, v3, v4
	v_cmp_ge_u32_e32 vcc, v4, v2
	v_add_u32_e32 v5, 1, v1
	s_nop 0
	v_cndmask_b32_e32 v1, v1, v5, vcc
	v_sub_u32_e32 v5, v4, v2
	v_cndmask_b32_e32 v4, v4, v5, vcc
	v_cmp_ge_u32_e32 vcc, v4, v2
	v_add_u32_e32 v4, 1, v1
	s_nop 0
	v_cndmask_b32_e32 v1, v1, v4, vcc
	v_add_u32_e32 v4, 1, v3
	v_mad_u64_u32 v[2:3], s[0:1], v2, v1, v[2:3]
	v_cmp_ne_u32_e32 vcc, v4, v2
	s_and_saveexec_b64 s[0:1], vcc
	s_xor_b64 s[8:9], exec, s[0:1]
	s_cbranch_execz .LBB0_255
	s_waitcnt vmcnt(0)
	v_mov_b32_e32 v3, 0x2000
	v_mov_b32_e32 v2, 1
	global_atomic_add v3, v2, s[6:7] offset:1024
	v_mad_u32_u24 v4, v1, v0, v0
	v_mov_b32_e32 v0, 0x3000
	global_load_dword v0, v0, s[92:93] offset:1024 sc1
	s_add_u32 s48, s92, 0x3400
	s_addc_u32 s49, s93, 0
	s_waitcnt vmcnt(0)
	v_cmp_lt_u32_e32 vcc, v0, v4
	s_and_saveexec_b64 s[12:13], vcc
	s_cbranch_execz .LBB0_254
	s_mov_b32 s0, 1
	s_mov_b64 s[56:57], 0
	v_mov_b32_e32 v0, 0
	s_branch .LBB0_245

.LBB0_413:
	s_or_b64 exec, exec, s[10:11]
	s_waitcnt vmcnt(0)
	buffer_inv sc1
	v_readfirstlane_b32 s0, v3
	v_sub_u32_e32 v4, 0, v2
	s_nop 0
	v_add_u32_e32 v3, s0, v1
	v_cvt_f32_u32_e32 v1, v2
	v_rcp_iflag_f32_e32 v1, v1
	s_nop 0
	v_mul_f32_e32 v1, 0x4f7ffffe, v1
	v_cvt_u32_f32_e32 v1, v1
	v_mul_lo_u32 v4, v4, v1
	v_mul_hi_u32 v4, v1, v4
	v_add_u32_e32 v1, v1, v4
	v_mul_hi_u32 v1, v3, v1
	v_mul_lo_u32 v4, v1, v2
	v_sub_u32_e32 v4, v3, v4
	v_cmp_ge_u32_e32 vcc, v4, v2
	v_add_u32_e32 v5, 1, v1
	s_nop 0
	v_cndmask_b32_e32 v1, v1, v5, vcc
	v_sub_u32_e32 v5, v4, v2
	v_cndmask_b32_e32 v4, v4, v5, vcc
	v_cmp_ge_u32_e32 vcc, v4, v2
	v_add_u32_e32 v4, 1, v1
	s_nop 0
	v_cndmask_b32_e32 v1, v1, v4, vcc
	v_add_u32_e32 v4, 1, v3
	v_mad_u64_u32 v[2:3], s[0:1], v2, v1, v[2:3]
	v_cmp_ne_u32_e32 vcc, v4, v2
	s_and_saveexec_b64 s[0:1], vcc
	s_xor_b64 s[8:9], exec, s[0:1]
	s_cbranch_execz .LBB0_427
	s_waitcnt vmcnt(0)
	v_mov_b32_e32 v3, 0x2000
	v_mov_b32_e32 v2, 1
	global_atomic_add v3, v2, s[6:7] offset:1024
	v_mad_u32_u24 v4, v1, v0, v0
	v_mov_b32_e32 v0, 0x3000
	global_load_dword v0, v0, s[92:93] offset:1024 sc1
	s_add_u32 s12, s92, 0x3400
	s_addc_u32 s13, s93, 0
	s_waitcnt vmcnt(0)
	v_cmp_lt_u32_e32 vcc, v0, v4
	s_and_saveexec_b64 s[10:11], vcc
	s_cbranch_execz .LBB0_426
	s_mov_b32 s0, 1
	s_mov_b64 s[48:49], 0
	v_mov_b32_e32 v0, 0
	s_branch .LBB0_417

.Lmy_xinv_done_4:
	v_mbcnt_lo_u32_b32 v1, s8, 0
	v_mbcnt_hi_u32_b32 v1, s9, v1
	v_cmp_eq_u32_e32 vcc, 0, v1
	s_and_saveexec_b64 s[10:11], vcc
	s_cbranch_execz .LBB0_430
	s_bcnt1_i32_b64 s0, s[8:9]
	v_mov_b32_e32 v2, 0x3000
	v_mov_b32_e32 v3, s0
	global_atomic_add v2, v2, v3, s[92:93] offset:1024 sc0

.LBB0_601:
	s_or_b64 exec, exec, s[22:23]
	v_cvt_f32_u32_e32 v4, v2
	s_waitcnt vmcnt(0)
	buffer_inv sc1
	v_readfirstlane_b32 s0, v3
	v_rcp_iflag_f32_e32 v4, v4
	s_nop 0
	v_add_u32_e32 v1, s0, v1
	v_add_u32_e32 v5, 1, v1
	v_mul_f32_e32 v3, 0x4f7ffffe, v4
	v_cvt_u32_f32_e32 v3, v3
	v_sub_u32_e32 v4, 0, v2
	v_mul_lo_u32 v4, v4, v3
	v_mul_hi_u32 v4, v3, v4
	v_add_u32_e32 v3, v3, v4
	v_mul_hi_u32 v3, v1, v3
	v_mul_lo_u32 v4, v3, v2
	v_sub_u32_e32 v1, v1, v4
	v_add_u32_e32 v6, 1, v3
	v_cmp_ge_u32_e32 vcc, v1, v2
	v_sub_u32_e32 v4, v1, v2
	s_nop 0
	v_cndmask_b32_e32 v3, v3, v6, vcc
	v_cndmask_b32_e32 v1, v1, v4, vcc
	v_add_u32_e32 v4, 1, v3
	v_cmp_ge_u32_e32 vcc, v1, v2
	s_nop 1
	v_cndmask_b32_e32 v1, v3, v4, vcc
	v_mad_u64_u32 v[2:3], s[0:1], v2, v1, v[2:3]
	v_cmp_ne_u32_e32 vcc, v5, v2
	s_and_saveexec_b64 s[0:1], vcc
	s_xor_b64 s[20:21], exec, s[0:1]
	s_cbranch_execz .LBB0_615
	s_waitcnt vmcnt(0)
	v_mov_b32_e32 v3, 0x2000
	v_mov_b32_e32 v2, 1
	global_atomic_add v3, v2, s[12:13] offset:1024
	v_mad_u32_u24 v5, v1, v0, v0
	v_mov_b32_e32 v0, 0x3000
	global_load_dword v0, v0, s[92:93] offset:1024 sc1
	s_add_u32 s48, s92, 0x3400
	s_addc_u32 s49, s93, 0
	s_waitcnt vmcnt(0)
	v_cmp_lt_u32_e32 vcc, v0, v5
	s_and_saveexec_b64 s[22:23], vcc
	s_cbranch_execz .LBB0_614
	s_mov_b32 s0, 1
	s_mov_b64 s[54:55], 0
	v_mov_b32_e32 v0, 0
	s_branch .LBB0_605

.LBB0_615:
	s_andn2_saveexec_b64 s[0:1], s[20:21]
	s_cbranch_execz .LBB0_635
	s_mov_b64 s[20:21], exec
	buffer_wbl2 sc1
	v_sub_u32_e32 v3, v2, v1
	v_mov_b32_e32 v4, 0x2000
	v_add_u32_e32 v3, -1, v3
	s_mov_b32 s98, 0x100000
.Lmy_xinv_5:
	global_load_dword v5, v4, s[12:13] offset:1024 sc1
	s_sub_u32 s98, s98, 1
	s_waitcnt lgkmcnt(0)
	s_waitcnt vmcnt(0)
	v_cmp_ge_u32_e32 vcc, v5, v3
	s_cbranch_vccnz .Lmy_xinv_done_5
	s_cmp_lg_u32 s98, 0
	s_cbranch_scc1 .Lmy_xinv_5
.Lmy_xinv_done_5:
	v_mbcnt_lo_u32_b32 v1, s20, 0
	v_mbcnt_hi_u32_b32 v1, s21, v1
	v_cmp_eq_u32_e32 vcc, 0, v1
	s_and_saveexec_b64 s[22:23], vcc
	s_cbranch_execz .LBB0_618
	s_bcnt1_i32_b64 s0, s[20:21]
	v_mov_b32_e32 v2, 0x3000
	v_mov_b32_e32 v3, s0
	global_atomic_add v2, v2, v3, s[92:93] offset:1024 sc0

.LBB0_688:
	s_or_b64 exec, exec, s[20:21]
	v_cvt_f32_u32_e32 v4, v2
	s_waitcnt vmcnt(0)
	buffer_inv sc1
	v_readfirstlane_b32 s0, v3
	v_rcp_iflag_f32_e32 v4, v4
	s_nop 0
	v_add_u32_e32 v1, s0, v1
	v_add_u32_e32 v5, 1, v1
	v_mul_f32_e32 v3, 0x4f7ffffe, v4
	v_cvt_u32_f32_e32 v3, v3
	v_sub_u32_e32 v4, 0, v2
	v_mul_lo_u32 v4, v4, v3
	v_mul_hi_u32 v4, v3, v4
	v_add_u32_e32 v3, v3, v4
	v_mul_hi_u32 v3, v1, v3
	v_mul_lo_u32 v4, v3, v2
	v_sub_u32_e32 v1, v1, v4
	v_add_u32_e32 v6, 1, v3
	v_cmp_ge_u32_e32 vcc, v1, v2
	v_sub_u32_e32 v4, v1, v2
	s_nop 0
	v_cndmask_b32_e32 v3, v3, v6, vcc
	v_cndmask_b32_e32 v1, v1, v4, vcc
	v_add_u32_e32 v4, 1, v3
	v_cmp_ge_u32_e32 vcc, v1, v2
	s_nop 1
	v_cndmask_b32_e32 v1, v3, v4, vcc
	v_mad_u64_u32 v[2:3], s[0:1], v2, v1, v[2:3]
	v_cmp_ne_u32_e32 vcc, v5, v2
	s_and_saveexec_b64 s[0:1], vcc
	s_xor_b64 s[16:17], exec, s[0:1]
	s_cbranch_execz .LBB0_702
	s_waitcnt vmcnt(0)
	v_mov_b32_e32 v3, 0x2000
	v_mov_b32_e32 v2, 1
	global_atomic_add v3, v2, s[12:13] offset:1024
	v_mad_u32_u24 v5, v1, v0, v0
	v_mov_b32_e32 v0, 0x3000
	global_load_dword v0, v0, s[92:93] offset:1024 sc1
	s_add_u32 s22, s92, 0x3400
	s_addc_u32 s23, s93, 0
	s_waitcnt vmcnt(0)
	v_cmp_lt_u32_e32 vcc, v0, v5
	s_and_saveexec_b64 s[20:21], vcc
	s_cbranch_execz .LBB0_701
	s_mov_b32 s0, 1
	s_mov_b64 s[24:25], 0
	v_mov_b32_e32 v0, 0
	s_branch .LBB0_692

.LBB0_702:
	s_andn2_saveexec_b64 s[0:1], s[16:17]
	s_cbranch_execz .LBB0_722
	s_mov_b64 s[16:17], exec
	buffer_wbl2 sc1
	v_sub_u32_e32 v3, v2, v1
	v_mov_b32_e32 v4, 0x2000
	v_add_u32_e32 v3, -1, v3
	s_mov_b32 s98, 0x100000

.Lmy_xinv_done_6:
	v_mbcnt_lo_u32_b32 v1, s16, 0
	v_mbcnt_hi_u32_b32 v1, s17, v1
	v_cmp_eq_u32_e32 vcc, 0, v1
	s_and_saveexec_b64 s[20:21], vcc
	s_cbranch_execz .LBB0_705
	s_bcnt1_i32_b64 s0, s[16:17]
	v_mov_b32_e32 v2, 0x3000
	v_mov_b32_e32 v3, s0
	global_atomic_add v2, v2, v3, s[92:93] offset:1024 sc0

.LBB0_788:
	s_or_b64 exec, exec, s[22:23]
	v_cvt_f32_u32_e32 v4, v2
	s_waitcnt vmcnt(0)
	buffer_inv sc1
	v_readfirstlane_b32 s0, v3
	v_rcp_iflag_f32_e32 v4, v4
	s_nop 0
	v_add_u32_e32 v1, s0, v1
	v_add_u32_e32 v5, 1, v1
	v_mul_f32_e32 v3, 0x4f7ffffe, v4
	v_cvt_u32_f32_e32 v3, v3
	v_sub_u32_e32 v4, 0, v2
	v_mul_lo_u32 v4, v4, v3
	v_mul_hi_u32 v4, v3, v4
	v_add_u32_e32 v3, v3, v4
	v_mul_hi_u32 v3, v1, v3
	v_mul_lo_u32 v4, v3, v2
	v_sub_u32_e32 v1, v1, v4
	v_add_u32_e32 v6, 1, v3
	v_cmp_ge_u32_e32 vcc, v1, v2
	v_sub_u32_e32 v4, v1, v2
	s_nop 0
	v_cndmask_b32_e32 v3, v3, v6, vcc
	v_cndmask_b32_e32 v1, v1, v4, vcc
	v_add_u32_e32 v4, 1, v3
	v_cmp_ge_u32_e32 vcc, v1, v2
	s_nop 1
	v_cndmask_b32_e32 v1, v3, v4, vcc
	v_mad_u64_u32 v[2:3], s[0:1], v2, v1, v[2:3]
	v_cmp_ne_u32_e32 vcc, v5, v2
	s_and_saveexec_b64 s[0:1], vcc
	s_xor_b64 s[20:21], exec, s[0:1]
	s_cbranch_execz .LBB0_802
	s_waitcnt vmcnt(0)
	v_mov_b32_e32 v3, 0x2000
	v_mov_b32_e32 v2, 1
	global_atomic_add v3, v2, s[16:17] offset:1024
	v_mad_u32_u24 v5, v1, v0, v0
	v_mov_b32_e32 v0, 0x3000
	global_load_dword v0, v0, s[92:93] offset:1024 sc1
	s_add_u32 s24, s92, 0x3400
	s_addc_u32 s25, s93, 0
	s_waitcnt vmcnt(0)
	v_cmp_lt_u32_e32 vcc, v0, v5
	s_and_saveexec_b64 s[22:23], vcc
	s_cbranch_execz .LBB0_801
	s_mov_b32 s0, 1
	s_mov_b64 s[26:27], 0
	v_mov_b32_e32 v0, 0
	s_branch .LBB0_792

.Lmy_xinv_7:
	global_load_dword v5, v4, s[16:17] offset:1024 sc1
	s_sub_u32 s98, s98, 1
	s_waitcnt lgkmcnt(0)
	s_waitcnt vmcnt(0)
	v_cmp_ge_u32_e32 vcc, v5, v3
	s_cbranch_vccnz .Lmy_xinv_done_7
	s_cmp_lg_u32 s98, 0
	s_cbranch_scc1 .Lmy_xinv_7

.LBB0_947:
	s_or_b64 exec, exec, s[10:11]
	v_cvt_f32_u32_e32 v4, v2
	s_waitcnt vmcnt(0)
	buffer_inv sc1
	v_readfirstlane_b32 s0, v3
	v_rcp_iflag_f32_e32 v4, v4
	s_nop 0
	v_add_u32_e32 v1, s0, v1
	v_add_u32_e32 v5, 1, v1
	v_mul_f32_e32 v3, 0x4f7ffffe, v4
	v_cvt_u32_f32_e32 v3, v3
	v_sub_u32_e32 v4, 0, v2
	v_mul_lo_u32 v4, v4, v3
	v_mul_hi_u32 v4, v3, v4
	v_add_u32_e32 v3, v3, v4
	v_mul_hi_u32 v3, v1, v3
	v_mul_lo_u32 v4, v3, v2
	v_sub_u32_e32 v1, v1, v4
	v_add_u32_e32 v6, 1, v3
	v_cmp_ge_u32_e32 vcc, v1, v2
	v_sub_u32_e32 v4, v1, v2
	s_nop 0
	v_cndmask_b32_e32 v3, v3, v6, vcc
	v_cndmask_b32_e32 v1, v1, v4, vcc
	v_add_u32_e32 v4, 1, v3
	v_cmp_ge_u32_e32 vcc, v1, v2
	s_nop 1
	v_cndmask_b32_e32 v1, v3, v4, vcc
	v_mad_u64_u32 v[2:3], s[0:1], v2, v1, v[2:3]
	v_cmp_ne_u32_e32 vcc, v5, v2
	s_and_saveexec_b64 s[0:1], vcc
	s_xor_b64 s[8:9], exec, s[0:1]
	s_cbranch_execz .LBB0_961
	s_waitcnt vmcnt(0)
	v_mov_b32_e32 v3, 0x2000
	v_mov_b32_e32 v2, 1
	global_atomic_add v3, v2, s[6:7] offset:1024
	v_mad_u32_u24 v5, v1, v0, v0
	v_mov_b32_e32 v0, 0x3000
	global_load_dword v0, v0, s[92:93] offset:1024 sc1
	s_add_u32 s12, s92, 0x3400
	s_addc_u32 s13, s93, 0
	s_waitcnt vmcnt(0)
	v_cmp_lt_u32_e32 vcc, v0, v5
	s_and_saveexec_b64 s[10:11], vcc
	s_cbranch_execz .LBB0_960
	s_mov_b32 s0, 1
	s_mov_b64 s[16:17], 0
	v_mov_b32_e32 v0, 0
	s_branch .LBB0_951

.LBB0_1004:
	s_or_b64 exec, exec, s[10:11]
	v_cvt_f32_u32_e32 v4, v2
	s_waitcnt vmcnt(0)
	buffer_inv sc1
	v_readfirstlane_b32 s0, v3
	v_rcp_iflag_f32_e32 v4, v4
	s_nop 0
	v_add_u32_e32 v1, s0, v1
	v_add_u32_e32 v5, 1, v1
	v_mul_f32_e32 v3, 0x4f7ffffe, v4
	v_cvt_u32_f32_e32 v3, v3
	v_sub_u32_e32 v4, 0, v2
	v_mul_lo_u32 v4, v4, v3
	v_mul_hi_u32 v4, v3, v4
	v_add_u32_e32 v3, v3, v4
	v_mul_hi_u32 v3, v1, v3
	v_mul_lo_u32 v4, v3, v2
	v_sub_u32_e32 v1, v1, v4
	v_add_u32_e32 v6, 1, v3
	v_cmp_ge_u32_e32 vcc, v1, v2
	v_sub_u32_e32 v4, v1, v2
	s_nop 0
	v_cndmask_b32_e32 v3, v3, v6, vcc
	v_cndmask_b32_e32 v1, v1, v4, vcc
	v_add_u32_e32 v4, 1, v3
	v_cmp_ge_u32_e32 vcc, v1, v2
	s_nop 1
	v_cndmask_b32_e32 v1, v3, v4, vcc
	v_mad_u64_u32 v[2:3], s[0:1], v2, v1, v[2:3]
	v_cmp_ne_u32_e32 vcc, v5, v2
	s_and_saveexec_b64 s[0:1], vcc
	s_xor_b64 s[8:9], exec, s[0:1]
	s_cbranch_execz .LBB0_1018
	s_waitcnt vmcnt(0)
	v_mov_b32_e32 v3, 0x2000
	v_mov_b32_e32 v2, 1
	global_atomic_add v3, v2, s[6:7] offset:1024
	v_mad_u32_u24 v5, v1, v0, v0
	v_mov_b32_e32 v0, 0x3000
	global_load_dword v0, v0, s[92:93] offset:1024 sc1
	s_add_u32 s12, s92, 0x3400
	s_addc_u32 s13, s93, 0
	s_waitcnt vmcnt(0)
	v_cmp_lt_u32_e32 vcc, v0, v5
	s_and_saveexec_b64 s[10:11], vcc
	s_cbranch_execz .LBB0_1017
	s_mov_b32 s0, 1
	s_mov_b64 s[14:15], 0
	v_mov_b32_e32 v0, 0
	s_branch .LBB0_1008
